# in-proj GEMM phase: workgroups start staggered over ~10 us so epilogue write bursts of different workgroups do not coincide
# speedup vs baseline: 1.0205x; 1.0072x over previous
;     __host__ __device__ bool next(int i, Unit& u) const {
;         const long L = (long)i * G + c; if (L >= nwg) return false;
;         int wgid = (int)L; { const int q = nwg / NXCD, r = nwg % NXCD, xcd = wgid % NXCD, off = wgid / NXCD; wgid = (xcd < r ? xcd * (q + 1) : r * (q + 1) + (xcd - r) * q) + off; }
;         const int nig = WGM * nN, gid = wgid / nig, fm = gid * WGM, gsz = (nM - fm) < WGM ? (nM - fm) : WGM;
;         u.pm = fm + ((wgid % nig) % gsz); u.pn = (wgid % nig) / gsz; return true;
; template <class Epi, class Sched, bool ALIGN_EPI = false, bool SP2 = false>
; __device__ __forceinline__ void gemm_phase(PG8_LAS unsigned char* lds, const Gemm g, const Sched& S, const Epi& E, const int tid) {
;     ...
;     if (!S.next(0, cur)) return;
.LBB0_465:
	s_and_b64 vcc, exec, s[6:7]
	s_cbranch_vccz .LBB0_652
	s_mul_i32 s98, s68, 37
	s_and_b32 s98, s98, 0xff
	s_lshr_b32 s98, s98, 3
.Lstag_inproj:
	s_cmp_eq_u32 s98, 0
	s_cbranch_scc1 .Lstag_inproj_done
	s_sleep 8
	s_sub_u32 s98, s98, 1
	s_branch .Lstag_inproj
.Lstag_inproj_done:
	s_cmpk_lt_i32 s68, 0x800
	s_cselect_b64 s[6:7], -1, 0
	s_cmpk_gt_i32 s68, 0x7ff
	v_readfirstlane_b32 s0, v210
	s_cbranch_scc1 .LBB0_472
	s_ashr_i32 s1, s68, 31
	s_lshr_b32 s1, s1, 29
	s_add_i32 s1, s68, s1
	s_and_b32 s2, s1, -8
	s_sub_i32 s2, s68, s2
	s_cmp_gt_i32 s2, -1
	s_mov_b64 s[8:9], -1
	s_cbranch_scc0 .LBB0_469
	s_lshl_b32 s10, s2, 8
	s_mov_b64 s[8:9], 0
